# v19 plus residual-row prefetch and counted waits in the three EpiRb GEMM epilogues
# baseline (speedup 1.0000x reference)
;     __device__ __forceinline__ void operator()(const f32x4 (&acc)[2][2][4][2], const Unit& u, int wr, int wc, int fr, int fq) const {
;     ...
; #pragma unroll
;         for (int ai = 0; ai < 2; ++ai)
; #pragma unroll
;             for (int m = 0; m < 4; ++m) { const int r = ai * HALF + wr * 64 + m * 16 + fr; bf16_t* rowp = xb + (size_t)(u.pm * BM + r) * ldc + col0; float q = 0.f;
;                 u32x4 bw[2];
; #pragma unroll
;                 for (int bj = 0; bj < 2; ++bj) bw[bj] = *(const u32x4*)(rowp + bj * HALF);
; #pragma unroll
;                 for (int bj = 0; bj < 2; ++bj) { const u32x4 b = bw[bj]; const f32x4 a0 = acc[ai][bj][m][0], a1 = acc[ai][bj][m][1];
;                     u32x4 w;
;                     w.x = pkbf(__uint_as_float(b.x << 16) + a0[0], __uint_as_float(b.x & 0xffff0000u) + a0[1]);
;                     w.y = pkbf(__uint_as_float(b.y << 16) + a0[2], __uint_as_float(b.y & 0xffff0000u) + a0[3]);
;                     w.z = pkbf(__uint_as_float(b.z << 16) + a1[0], __uint_as_float(b.z & 0xffff0000u) + a1[1]);
;                     w.w = pkbf(__uint_as_float(b.w << 16) + a1[2], __uint_as_float(b.w & 0xffff0000u) + a1[3]);
;                     *(u32x4*)(rowp + bj * HALF) = w;
;                     if (NORM) {
; #pragma unroll
;                         for (int e = 0; e < 4; ++e) { const float lo = __uint_as_float(w[e] << 16), hi = __uint_as_float(w[e] & 0xffff0000u); q += lo * lo + hi * hi; } } }
;                 if (NORM) { q += __shfl_xor(q, 16); q += __shfl_xor(q, 32); if (fq == 0) ss[(size_t)(u.pm * BM + r) * 16 + u.pn * 4 + wc] = q; } }
.LBB0_430:
	v_lshl_add_u32 v146, s26, 8, v148
	v_ashrrev_i32_e32 v147, 31, v146
	v_lshl_or_b32 v144, s0, 8, v150
	v_lshlrev_b64 v[156:157], 11, v[146:147]
	v_ashrrev_i32_e32 v145, 31, v144
	v_lshl_add_u64 v[156:157], s[40:41], 0, v[156:157]
	v_lshl_add_u64 v[164:165], v[144:145], 1, v[156:157]
	global_load_dwordx4 v[156:159], v[164:165], off
	global_load_dwordx4 v[160:163], v[164:165], off offset:256
	v_add_co_u32_e32 v244, vcc, 0x8000, v164
	s_nop 1
	v_addc_co_u32_e32 v245, vcc, 0, v165, vcc
	global_load_dwordx4 v[180:183], v[244:245], off
	global_load_dwordx4 v[184:187], v[244:245], off offset:256
	v_add_co_u32_e32 v244, vcc, 0x10000, v164
	s_nop 1
	v_addc_co_u32_e32 v245, vcc, 0, v165, vcc
	global_load_dwordx4 v[188:191], v[244:245], off
	global_load_dwordx4 v[192:195], v[244:245], off offset:256
	v_add_co_u32_e32 v244, vcc, 0x18000, v164
	s_nop 1
	v_addc_co_u32_e32 v245, vcc, 0, v165, vcc
	global_load_dwordx4 v[196:199], v[244:245], off
	global_load_dwordx4 v[200:203], v[244:245], off offset:256
	v_add_co_u32_e32 v244, vcc, 0x40000, v164
	s_nop 1
	v_addc_co_u32_e32 v245, vcc, 0, v165, vcc
	global_load_dwordx4 v[204:207], v[244:245], off
	global_load_dwordx4 v[208:211], v[244:245], off offset:256
	v_add_co_u32_e32 v244, vcc, 0x48000, v164
	s_nop 1
	v_addc_co_u32_e32 v245, vcc, 0, v165, vcc
	global_load_dwordx4 v[228:231], v[244:245], off
	global_load_dwordx4 v[232:235], v[244:245], off offset:256
	v_add_co_u32_e32 v244, vcc, 0x50000, v164
	s_nop 1
	v_addc_co_u32_e32 v245, vcc, 0, v165, vcc
	global_load_dwordx4 v[236:239], v[244:245], off
	global_load_dwordx4 v[240:243], v[244:245], off offset:256
	v_and_b32_e32 v166, 64, v154
	v_add_u32_e32 v174, 64, v166
	v_xor_b32_e32 v155, 16, v154
	v_cmp_lt_i32_e32 vcc, v155, v174
	s_lshl_b32 s26, s0, 2
	s_ashr_i32 s27, s26, 31
	v_cndmask_b32_e32 v155, v154, v155, vcc
	v_lshlrev_b32_e32 v155, 2, v155
	s_waitcnt vmcnt(12)
	v_lshlrev_b32_e32 v166, 16, v156
	v_and_b32_e32 v167, 0xffff0000, v156
	v_lshlrev_b32_e32 v156, 16, v157
	v_and_b32_e32 v157, 0xffff0000, v157
	v_lshlrev_b32_e32 v168, 16, v158
	v_and_b32_e32 v169, 0xffff0000, v158
	v_lshlrev_b32_e32 v158, 16, v159
	v_and_b32_e32 v159, 0xffff0000, v159
	v_lshlrev_b32_e32 v170, 16, v160
	v_and_b32_e32 v171, 0xffff0000, v160
	v_lshlrev_b32_e32 v172, 16, v162
	v_and_b32_e32 v173, 0xffff0000, v162
	v_lshlrev_b32_e32 v162, 16, v163
	v_and_b32_e32 v163, 0xffff0000, v163
	v_pk_add_f32 v[124:125], v[124:125], v[166:167]
	v_pk_add_f32 v[126:127], v[126:127], v[156:157]
	v_lshlrev_b32_e32 v160, 16, v161
	v_and_b32_e32 v161, 0xffff0000, v161
	v_pk_add_f32 v[120:121], v[120:121], v[168:169]
	v_pk_add_f32 v[122:123], v[122:123], v[158:159]
	v_pk_add_f32 v[156:157], v[116:117], v[170:171]
	v_pk_add_f32 v[112:113], v[112:113], v[172:173]
	v_pk_add_f32 v[114:115], v[114:115], v[162:163]
	v_cvt_pk_bf16_f32 v116, v124, v125
	v_cvt_pk_bf16_f32 v117, v126, v127
	v_pk_add_f32 v[158:159], v[118:119], v[160:161]
	v_cvt_pk_bf16_f32 v118, v120, v121
	v_cvt_pk_bf16_f32 v119, v122, v123
	v_cvt_pk_bf16_f32 v122, v112, v113
	v_cvt_pk_bf16_f32 v123, v114, v115
	v_and_b32_e32 v113, 0xffff0000, v116
	v_and_b32_e32 v115, 0xffff0000, v117
	v_lshlrev_b32_e32 v112, 16, v116
	v_lshlrev_b32_e32 v114, 16, v117
	v_and_b32_e32 v125, 0xffff0000, v118
	v_mul_f32_e32 v113, v113, v113
	v_mul_f32_e32 v115, v115, v115
	v_cvt_pk_bf16_f32 v120, v156, v157
	v_lshlrev_b32_e32 v124, 16, v118
	v_and_b32_e32 v127, 0xffff0000, v119
	v_mul_f32_e32 v125, v125, v125
	v_fmac_f32_e32 v113, v112, v112
	v_fmac_f32_e32 v115, v114, v114
	v_cvt_pk_bf16_f32 v121, v158, v159
	v_lshlrev_b32_e32 v126, 16, v119
	v_and_b32_e32 v157, 0xffff0000, v120
	v_mul_f32_e32 v127, v127, v127
	v_fmac_f32_e32 v125, v124, v124
	v_add_f32_e32 v112, v113, v115
	v_lshlrev_b32_e32 v156, 16, v120
	v_and_b32_e32 v159, 0xffff0000, v121
	v_mul_f32_e32 v157, v157, v157
	v_fmac_f32_e32 v127, v126, v126
	v_add_f32_e32 v112, v125, v112
	v_lshlrev_b32_e32 v158, 16, v121
	v_and_b32_e32 v161, 0xffff0000, v122
	v_mul_f32_e32 v159, v159, v159
	v_fmac_f32_e32 v157, v156, v156
	v_add_f32_e32 v112, v127, v112
	v_lshlrev_b32_e32 v160, 16, v122
	v_and_b32_e32 v163, 0xffff0000, v123
	v_mul_f32_e32 v161, v161, v161
	v_fmac_f32_e32 v159, v158, v158
	v_add_f32_e32 v112, v157, v112
	v_lshlrev_b32_e32 v162, 16, v123
	v_mul_f32_e32 v163, v163, v163
	v_fmac_f32_e32 v161, v160, v160
	v_add_f32_e32 v112, v159, v112
	v_add_f32_e32 v112, v161, v112
	v_fmac_f32_e32 v163, v162, v162
	v_add_f32_e32 v112, v163, v112
	ds_bpermute_b32 v113, v155, v112
	v_xor_b32_e32 v114, 32, v154
	v_cmp_lt_i32_e32 vcc, v114, v174
	global_store_dwordx4 v[164:165], v[116:119], off
	global_store_dwordx4 v[164:165], v[120:123], off offset:256
	v_cndmask_b32_e32 v114, v154, v114, vcc
	v_lshlrev_b32_e32 v114, 2, v114
	s_waitcnt lgkmcnt(0)
	v_add_f32_e32 v112, v112, v113
	ds_bpermute_b32 v113, v114, v112
	s_and_saveexec_b64 s[2:3], s[4:5]
	s_cbranch_execz .LBB0_432
	v_lshlrev_b64 v[116:117], 6, v[146:147]
	v_lshl_add_u64 v[116:117], s[20:21], 0, v[116:117]
	v_lshl_add_u64 v[116:117], s[26:27], 2, v[116:117]
	s_lshl_b32 s0, s42, 2
	v_lshl_add_u64 v[116:117], v[116:117], 0, s[0:1]
	s_waitcnt lgkmcnt(0)
	v_add_f32_e32 v112, v112, v113
	global_store_dword v[116:117], v112, off
;     __device__ __forceinline__ void operator()(const f32x4 (&acc)[2][2][4][2], const Unit& u, int wr, int wc, int fr, int fq) const {
;     ...
; #pragma unroll
;         for (int ai = 0; ai < 2; ++ai)
; #pragma unroll
;             for (int m = 0; m < 4; ++m) { const int r = ai * HALF + wr * 64 + m * 16 + fr; bf16_t* rowp = xb + (size_t)(u.pm * BM + r) * ldc + col0; float q = 0.f;
;                 u32x4 bw[2];
; #pragma unroll
;                 for (int bj = 0; bj < 2; ++bj) bw[bj] = *(const u32x4*)(rowp + bj * HALF);
; #pragma unroll
;                 for (int bj = 0; bj < 2; ++bj) { const u32x4 b = bw[bj]; const f32x4 a0 = acc[ai][bj][m][0], a1 = acc[ai][bj][m][1];
;                     u32x4 w;
;                     w.x = pkbf(__uint_as_float(b.x << 16) + a0[0], __uint_as_float(b.x & 0xffff0000u) + a0[1]);
;                     w.y = pkbf(__uint_as_float(b.y << 16) + a0[2], __uint_as_float(b.y & 0xffff0000u) + a0[3]);
;                     w.z = pkbf(__uint_as_float(b.z << 16) + a1[0], __uint_as_float(b.z & 0xffff0000u) + a1[1]);
;                     w.w = pkbf(__uint_as_float(b.w << 16) + a1[2], __uint_as_float(b.w & 0xffff0000u) + a1[3]);
;                     *(u32x4*)(rowp + bj * HALF) = w;
;                     if (NORM) {
; #pragma unroll
;                         for (int e = 0; e < 4; ++e) { const float lo = __uint_as_float(w[e] << 16), hi = __uint_as_float(w[e] & 0xffff0000u); q += lo * lo + hi * hi; } } }
;                 if (NORM) { q += __shfl_xor(q, 16); q += __shfl_xor(q, 32); if (fq == 0) ss[(size_t)(u.pm * BM + r) * 16 + u.pn * 4 + wc] = q; } }
.LBB0_432:
	s_or_b64 exec, exec, s[2:3]
	v_or_b32_e32 v112, 16, v146
	s_waitcnt lgkmcnt(0)
	v_ashrrev_i32_e32 v113, 31, v112
	v_lshlrev_b64 v[116:117], 11, v[112:113]
	v_lshl_add_u64 v[116:117], s[40:41], 0, v[116:117]
	v_lshl_add_u64 v[124:125], v[144:145], 1, v[116:117]
	s_waitcnt vmcnt(14)
	v_lshlrev_b32_e32 v126, 16, v180
	v_and_b32_e32 v127, 0xffff0000, v180
	v_lshlrev_b32_e32 v180, 16, v181
	v_and_b32_e32 v181, 0xffff0000, v181
	v_lshlrev_b32_e32 v156, 16, v182
	v_and_b32_e32 v157, 0xffff0000, v182
	v_lshlrev_b32_e32 v182, 16, v183
	v_and_b32_e32 v183, 0xffff0000, v183
	s_waitcnt vmcnt(13)
	v_lshlrev_b32_e32 v158, 16, v184
	v_and_b32_e32 v159, 0xffff0000, v184
	v_lshlrev_b32_e32 v184, 16, v185
	v_and_b32_e32 v185, 0xffff0000, v185
	v_lshlrev_b32_e32 v160, 16, v186
	v_and_b32_e32 v161, 0xffff0000, v186
	v_lshlrev_b32_e32 v186, 16, v187
	v_and_b32_e32 v187, 0xffff0000, v187
	v_pk_add_f32 v[108:109], v[108:109], v[126:127]
	v_pk_add_f32 v[110:111], v[110:111], v[180:181]
	v_pk_add_f32 v[104:105], v[104:105], v[156:157]
	v_pk_add_f32 v[106:107], v[106:107], v[182:183]
	v_pk_add_f32 v[182:183], v[102:103], v[184:185]
	v_pk_add_f32 v[96:97], v[96:97], v[160:161]
	v_pk_add_f32 v[184:185], v[98:99], v[186:187]
	v_cvt_pk_bf16_f32 v98, v108, v109
	v_cvt_pk_bf16_f32 v99, v110, v111
	v_pk_add_f32 v[180:181], v[100:101], v[158:159]
	v_cvt_pk_bf16_f32 v100, v104, v105
	v_cvt_pk_bf16_f32 v101, v106, v107
	v_cvt_pk_bf16_f32 v104, v96, v97
	v_and_b32_e32 v97, 0xffff0000, v98
	v_and_b32_e32 v107, 0xffff0000, v99
	v_lshlrev_b32_e32 v96, 16, v98
	v_lshlrev_b32_e32 v106, 16, v99
	v_and_b32_e32 v109, 0xffff0000, v100
	v_mul_f32_e32 v97, v97, v97
	v_mul_f32_e32 v107, v107, v107
	v_cvt_pk_bf16_f32 v102, v180, v181
	v_lshlrev_b32_e32 v108, 16, v100
	v_and_b32_e32 v111, 0xffff0000, v101
	v_mul_f32_e32 v109, v109, v109
	v_fmac_f32_e32 v97, v96, v96
	v_fmac_f32_e32 v107, v106, v106
	v_cvt_pk_bf16_f32 v103, v182, v183
	v_lshlrev_b32_e32 v110, 16, v101
	v_and_b32_e32 v180, 0xffff0000, v102
	v_mul_f32_e32 v111, v111, v111
	v_fmac_f32_e32 v109, v108, v108
	v_add_f32_e32 v96, v97, v107
	v_lshlrev_b32_e32 v115, 16, v102
	v_and_b32_e32 v182, 0xffff0000, v103
	v_mul_f32_e32 v180, v180, v180
	v_fmac_f32_e32 v111, v110, v110
	v_add_f32_e32 v96, v109, v96
	v_cvt_pk_bf16_f32 v105, v184, v185
	v_lshlrev_b32_e32 v181, 16, v103
	v_and_b32_e32 v184, 0xffff0000, v104
	v_mul_f32_e32 v182, v182, v182
	v_fmac_f32_e32 v180, v115, v115
	v_add_f32_e32 v96, v111, v96
	v_lshlrev_b32_e32 v183, 16, v104
	v_and_b32_e32 v186, 0xffff0000, v105
	v_mul_f32_e32 v184, v184, v184
	v_fmac_f32_e32 v182, v181, v181
	v_add_f32_e32 v96, v180, v96
	v_lshlrev_b32_e32 v185, 16, v105
	v_mul_f32_e32 v186, v186, v186
	v_fmac_f32_e32 v184, v183, v183
	v_add_f32_e32 v96, v182, v96
	v_add_f32_e32 v96, v184, v96
	v_fmac_f32_e32 v186, v185, v185
	v_add_f32_e32 v96, v186, v96
	ds_bpermute_b32 v97, v155, v96
	global_store_dwordx4 v[124:125], v[98:101], off
	global_store_dwordx4 v[124:125], v[102:105], off offset:256
	s_waitcnt lgkmcnt(0)
	v_add_f32_e32 v96, v96, v97
	ds_bpermute_b32 v97, v114, v96
	s_and_saveexec_b64 s[2:3], s[4:5]
	s_cbranch_execz .LBB0_434
	v_lshlrev_b64 v[98:99], 6, v[112:113]
	v_lshl_add_u64 v[98:99], s[20:21], 0, v[98:99]
	v_lshl_add_u64 v[98:99], s[26:27], 2, v[98:99]
	s_lshl_b32 s0, s42, 2
	v_lshl_add_u64 v[98:99], v[98:99], 0, s[0:1]
	s_waitcnt lgkmcnt(0)
	v_add_f32_e32 v96, v96, v97
	global_store_dword v[98:99], v96, off
.LBB0_434:
	s_or_b64 exec, exec, s[2:3]
	v_or_b32_e32 v96, 32, v146
	s_waitcnt lgkmcnt(0)
	v_ashrrev_i32_e32 v97, 31, v96
	v_lshlrev_b64 v[98:99], 11, v[96:97]
	v_lshl_add_u64 v[98:99], s[40:41], 0, v[98:99]
	v_lshl_add_u64 v[106:107], v[144:145], 1, v[98:99]
	s_waitcnt vmcnt(15)
	v_lshlrev_b32_e32 v108, 16, v188
	v_and_b32_e32 v109, 0xffff0000, v188
	v_lshlrev_b32_e32 v188, 16, v189
	v_and_b32_e32 v189, 0xffff0000, v189
	v_lshlrev_b32_e32 v110, 16, v190
	v_and_b32_e32 v111, 0xffff0000, v190
	v_lshlrev_b32_e32 v190, 16, v191
	v_and_b32_e32 v191, 0xffff0000, v191
	s_waitcnt vmcnt(14)
	v_lshlrev_b32_e32 v112, 16, v192
	v_and_b32_e32 v113, 0xffff0000, v192
	v_lshlrev_b32_e32 v192, 16, v193
	v_and_b32_e32 v193, 0xffff0000, v193
	v_lshlrev_b32_e32 v116, 16, v194
	v_and_b32_e32 v117, 0xffff0000, v194
	v_lshlrev_b32_e32 v194, 16, v195
	v_and_b32_e32 v195, 0xffff0000, v195
	v_pk_add_f32 v[92:93], v[92:93], v[108:109]
	v_pk_add_f32 v[94:95], v[94:95], v[188:189]
	v_pk_add_f32 v[88:89], v[88:89], v[110:111]
	v_pk_add_f32 v[90:91], v[90:91], v[190:191]
	v_pk_add_f32 v[190:191], v[86:87], v[192:193]
	v_pk_add_f32 v[80:81], v[80:81], v[116:117]
	v_pk_add_f32 v[192:193], v[82:83], v[194:195]
	v_cvt_pk_bf16_f32 v82, v92, v93
	v_cvt_pk_bf16_f32 v83, v94, v95
	v_pk_add_f32 v[188:189], v[84:85], v[112:113]
	v_cvt_pk_bf16_f32 v84, v88, v89
	v_cvt_pk_bf16_f32 v85, v90, v91
	v_cvt_pk_bf16_f32 v88, v80, v81
	v_and_b32_e32 v81, 0xffff0000, v82
	v_and_b32_e32 v91, 0xffff0000, v83
	v_lshlrev_b32_e32 v80, 16, v82
	v_lshlrev_b32_e32 v90, 16, v83
	v_and_b32_e32 v93, 0xffff0000, v84
	v_mul_f32_e32 v81, v81, v81
	v_mul_f32_e32 v91, v91, v91
	v_cvt_pk_bf16_f32 v86, v188, v189
	v_lshlrev_b32_e32 v92, 16, v84
	v_and_b32_e32 v95, 0xffff0000, v85
	v_mul_f32_e32 v93, v93, v93
	v_fmac_f32_e32 v81, v80, v80
	v_fmac_f32_e32 v91, v90, v90
	v_cvt_pk_bf16_f32 v87, v190, v191
	v_lshlrev_b32_e32 v94, 16, v85
	v_and_b32_e32 v189, 0xffff0000, v86
	v_mul_f32_e32 v95, v95, v95
	v_fmac_f32_e32 v93, v92, v92
	v_add_f32_e32 v80, v81, v91
	v_lshlrev_b32_e32 v188, 16, v86
	v_and_b32_e32 v191, 0xffff0000, v87
	v_mul_f32_e32 v189, v189, v189
	v_fmac_f32_e32 v95, v94, v94
	v_add_f32_e32 v80, v93, v80
	v_cvt_pk_bf16_f32 v89, v192, v193
	v_lshlrev_b32_e32 v190, 16, v87
	v_and_b32_e32 v193, 0xffff0000, v88
	v_mul_f32_e32 v191, v191, v191
	v_fmac_f32_e32 v189, v188, v188
	v_add_f32_e32 v80, v95, v80
	v_lshlrev_b32_e32 v192, 16, v88
	v_and_b32_e32 v195, 0xffff0000, v89
	v_mul_f32_e32 v193, v193, v193
	v_fmac_f32_e32 v191, v190, v190
	v_add_f32_e32 v80, v189, v80
	v_lshlrev_b32_e32 v194, 16, v89
	v_mul_f32_e32 v195, v195, v195
	v_fmac_f32_e32 v193, v192, v192
	v_add_f32_e32 v80, v191, v80
	v_add_f32_e32 v80, v193, v80
	v_fmac_f32_e32 v195, v194, v194
	v_add_f32_e32 v80, v195, v80
	ds_bpermute_b32 v81, v155, v80
	global_store_dwordx4 v[106:107], v[82:85], off
	global_store_dwordx4 v[106:107], v[86:89], off offset:256
	s_waitcnt lgkmcnt(0)
	v_add_f32_e32 v80, v80, v81
	ds_bpermute_b32 v81, v114, v80
	s_and_saveexec_b64 s[2:3], s[4:5]
	s_cbranch_execz .LBB0_436
	v_lshlrev_b64 v[82:83], 6, v[96:97]
	v_lshl_add_u64 v[82:83], s[20:21], 0, v[82:83]
	v_lshl_add_u64 v[82:83], s[26:27], 2, v[82:83]
	s_lshl_b32 s0, s42, 2
	v_lshl_add_u64 v[82:83], v[82:83], 0, s[0:1]
	s_waitcnt lgkmcnt(0)
	v_add_f32_e32 v80, v80, v81
	global_store_dword v[82:83], v80, off
;     __device__ __forceinline__ void operator()(const f32x4 (&acc)[2][2][4][2], const Unit& u, int wr, int wc, int fr, int fq) const {
;     ...
; #pragma unroll
;         for (int ai = 0; ai < 2; ++ai)
; #pragma unroll
;             for (int m = 0; m < 4; ++m) { const int r = ai * HALF + wr * 64 + m * 16 + fr; bf16_t* rowp = xb + (size_t)(u.pm * BM + r) * ldc + col0; float q = 0.f;
;                 u32x4 bw[2];
; #pragma unroll
;                 for (int bj = 0; bj < 2; ++bj) bw[bj] = *(const u32x4*)(rowp + bj * HALF);
; #pragma unroll
;                 for (int bj = 0; bj < 2; ++bj) { const u32x4 b = bw[bj]; const f32x4 a0 = acc[ai][bj][m][0], a1 = acc[ai][bj][m][1];
;                     u32x4 w;
;                     w.x = pkbf(__uint_as_float(b.x << 16) + a0[0], __uint_as_float(b.x & 0xffff0000u) + a0[1]);
;                     w.y = pkbf(__uint_as_float(b.y << 16) + a0[2], __uint_as_float(b.y & 0xffff0000u) + a0[3]);
;                     w.z = pkbf(__uint_as_float(b.z << 16) + a1[0], __uint_as_float(b.z & 0xffff0000u) + a1[1]);
;                     w.w = pkbf(__uint_as_float(b.w << 16) + a1[2], __uint_as_float(b.w & 0xffff0000u) + a1[3]);
;                     *(u32x4*)(rowp + bj * HALF) = w;
;                     if (NORM) {
; #pragma unroll
;                         for (int e = 0; e < 4; ++e) { const float lo = __uint_as_float(w[e] << 16), hi = __uint_as_float(w[e] & 0xffff0000u); q += lo * lo + hi * hi; } } }
;                 if (NORM) { q += __shfl_xor(q, 16); q += __shfl_xor(q, 32); if (fq == 0) ss[(size_t)(u.pm * BM + r) * 16 + u.pn * 4 + wc] = q; } }
.LBB0_436:
	s_or_b64 exec, exec, s[2:3]
	v_or_b32_e32 v80, 48, v146
	s_waitcnt lgkmcnt(0)
	v_ashrrev_i32_e32 v81, 31, v80
	v_lshlrev_b64 v[82:83], 11, v[80:81]
	v_lshl_add_u64 v[82:83], s[40:41], 0, v[82:83]
	v_lshl_add_u64 v[90:91], v[144:145], 1, v[82:83]
	s_waitcnt vmcnt(16)
	v_lshlrev_b32_e32 v92, 16, v196
	v_and_b32_e32 v93, 0xffff0000, v196
	v_lshlrev_b32_e32 v196, 16, v197
	v_and_b32_e32 v197, 0xffff0000, v197
	v_lshlrev_b32_e32 v94, 16, v198
	v_and_b32_e32 v95, 0xffff0000, v198
	v_lshlrev_b32_e32 v198, 16, v199
	v_and_b32_e32 v199, 0xffff0000, v199
	s_waitcnt vmcnt(15)
	v_lshlrev_b32_e32 v96, 16, v200
	v_and_b32_e32 v97, 0xffff0000, v200
	v_lshlrev_b32_e32 v200, 16, v201
	v_and_b32_e32 v201, 0xffff0000, v201
	v_lshlrev_b32_e32 v98, 16, v202
	v_and_b32_e32 v99, 0xffff0000, v202
	v_lshlrev_b32_e32 v202, 16, v203
	v_and_b32_e32 v203, 0xffff0000, v203
	v_pk_add_f32 v[76:77], v[76:77], v[92:93]
	v_pk_add_f32 v[78:79], v[78:79], v[196:197]
	v_pk_add_f32 v[72:73], v[72:73], v[94:95]
	v_pk_add_f32 v[74:75], v[74:75], v[198:199]
	v_pk_add_f32 v[198:199], v[70:71], v[200:201]
	v_pk_add_f32 v[64:65], v[64:65], v[98:99]
	v_pk_add_f32 v[200:201], v[66:67], v[202:203]
	v_cvt_pk_bf16_f32 v66, v76, v77
	v_cvt_pk_bf16_f32 v67, v78, v79
	v_pk_add_f32 v[196:197], v[68:69], v[96:97]
	v_cvt_pk_bf16_f32 v68, v72, v73
	v_cvt_pk_bf16_f32 v69, v74, v75
	v_cvt_pk_bf16_f32 v72, v64, v65
	v_and_b32_e32 v65, 0xffff0000, v66
	v_and_b32_e32 v75, 0xffff0000, v67
	v_lshlrev_b32_e32 v64, 16, v66
	v_lshlrev_b32_e32 v74, 16, v67
	v_and_b32_e32 v77, 0xffff0000, v68
	v_mul_f32_e32 v65, v65, v65
	v_mul_f32_e32 v75, v75, v75
	v_cvt_pk_bf16_f32 v70, v196, v197
	v_lshlrev_b32_e32 v76, 16, v68
	v_and_b32_e32 v79, 0xffff0000, v69
	v_mul_f32_e32 v77, v77, v77
	v_fmac_f32_e32 v65, v64, v64
	v_fmac_f32_e32 v75, v74, v74
	v_cvt_pk_bf16_f32 v71, v198, v199
	v_lshlrev_b32_e32 v78, 16, v69
	v_and_b32_e32 v197, 0xffff0000, v70
	v_mul_f32_e32 v79, v79, v79
	v_fmac_f32_e32 v77, v76, v76
	v_add_f32_e32 v64, v65, v75
	v_lshlrev_b32_e32 v196, 16, v70
	v_and_b32_e32 v199, 0xffff0000, v71
	v_mul_f32_e32 v197, v197, v197
	v_fmac_f32_e32 v79, v78, v78
	v_add_f32_e32 v64, v77, v64
	v_cvt_pk_bf16_f32 v73, v200, v201
	v_lshlrev_b32_e32 v198, 16, v71
	v_and_b32_e32 v201, 0xffff0000, v72
	v_mul_f32_e32 v199, v199, v199
	v_fmac_f32_e32 v197, v196, v196
	v_add_f32_e32 v64, v79, v64
	v_lshlrev_b32_e32 v200, 16, v72
	v_and_b32_e32 v203, 0xffff0000, v73
	v_mul_f32_e32 v201, v201, v201
	v_fmac_f32_e32 v199, v198, v198
	v_add_f32_e32 v64, v197, v64
	v_lshlrev_b32_e32 v202, 16, v73
	v_mul_f32_e32 v203, v203, v203
	v_fmac_f32_e32 v201, v200, v200
	v_add_f32_e32 v64, v199, v64
	v_add_f32_e32 v64, v201, v64
	v_fmac_f32_e32 v203, v202, v202
	v_add_f32_e32 v64, v203, v64
	ds_bpermute_b32 v65, v155, v64
	global_store_dwordx4 v[90:91], v[66:69], off
	global_store_dwordx4 v[90:91], v[70:73], off offset:256
	s_waitcnt lgkmcnt(0)
	v_add_f32_e32 v64, v64, v65
	ds_bpermute_b32 v65, v114, v64
	s_and_saveexec_b64 s[2:3], s[4:5]
	s_cbranch_execz .LBB0_438
	v_lshlrev_b64 v[66:67], 6, v[80:81]
	v_lshl_add_u64 v[66:67], s[20:21], 0, v[66:67]
	v_lshl_add_u64 v[66:67], s[26:27], 2, v[66:67]
	s_lshl_b32 s0, s42, 2
	v_lshl_add_u64 v[66:67], v[66:67], 0, s[0:1]
	s_waitcnt lgkmcnt(0)
	v_add_f32_e32 v64, v64, v65
	global_store_dword v[66:67], v64, off
.LBB0_438:
	s_or_b64 exec, exec, s[2:3]
	v_add_u32_e32 v64, 0x80, v146
	s_waitcnt lgkmcnt(0)
	v_ashrrev_i32_e32 v65, 31, v64
	v_lshlrev_b64 v[66:67], 11, v[64:65]
	v_lshl_add_u64 v[66:67], s[40:41], 0, v[66:67]
	v_lshl_add_u64 v[74:75], v[144:145], 1, v[66:67]
	s_waitcnt vmcnt(17)
	v_lshlrev_b32_e32 v76, 16, v204
	v_and_b32_e32 v77, 0xffff0000, v204
	v_lshlrev_b32_e32 v204, 16, v205
	v_and_b32_e32 v205, 0xffff0000, v205
	v_lshlrev_b32_e32 v78, 16, v206
	v_and_b32_e32 v79, 0xffff0000, v206
	v_lshlrev_b32_e32 v206, 16, v207
	v_and_b32_e32 v207, 0xffff0000, v207
	s_waitcnt vmcnt(16)
	v_lshlrev_b32_e32 v80, 16, v208
	v_and_b32_e32 v81, 0xffff0000, v208
	v_lshlrev_b32_e32 v208, 16, v209
	v_and_b32_e32 v209, 0xffff0000, v209
	v_lshlrev_b32_e32 v82, 16, v210
	v_and_b32_e32 v83, 0xffff0000, v210
	v_lshlrev_b32_e32 v210, 16, v211
	v_and_b32_e32 v211, 0xffff0000, v211
	v_pk_add_f32 v[60:61], v[60:61], v[76:77]
	v_pk_add_f32 v[62:63], v[62:63], v[204:205]
	v_pk_add_f32 v[56:57], v[56:57], v[78:79]
	v_pk_add_f32 v[58:59], v[58:59], v[206:207]
	v_pk_add_f32 v[206:207], v[54:55], v[208:209]
	v_pk_add_f32 v[48:49], v[48:49], v[82:83]
	v_pk_add_f32 v[208:209], v[50:51], v[210:211]
	v_cvt_pk_bf16_f32 v50, v60, v61
	v_cvt_pk_bf16_f32 v51, v62, v63
	v_pk_add_f32 v[204:205], v[52:53], v[80:81]
	v_cvt_pk_bf16_f32 v52, v56, v57
	v_cvt_pk_bf16_f32 v53, v58, v59
	v_cvt_pk_bf16_f32 v56, v48, v49
	v_and_b32_e32 v49, 0xffff0000, v50
	v_and_b32_e32 v59, 0xffff0000, v51
	v_lshlrev_b32_e32 v48, 16, v50
	v_lshlrev_b32_e32 v58, 16, v51
	v_and_b32_e32 v61, 0xffff0000, v52
	v_mul_f32_e32 v49, v49, v49
	v_mul_f32_e32 v59, v59, v59
	v_cvt_pk_bf16_f32 v54, v204, v205
	v_lshlrev_b32_e32 v60, 16, v52
	v_and_b32_e32 v63, 0xffff0000, v53
	v_mul_f32_e32 v61, v61, v61
	v_fmac_f32_e32 v49, v48, v48
	v_fmac_f32_e32 v59, v58, v58
	v_cvt_pk_bf16_f32 v55, v206, v207
	v_lshlrev_b32_e32 v62, 16, v53
	v_and_b32_e32 v205, 0xffff0000, v54
	v_mul_f32_e32 v63, v63, v63
	v_fmac_f32_e32 v61, v60, v60
	v_add_f32_e32 v48, v49, v59
	v_lshlrev_b32_e32 v204, 16, v54
	v_and_b32_e32 v207, 0xffff0000, v55
	v_mul_f32_e32 v205, v205, v205
	v_fmac_f32_e32 v63, v62, v62
	v_add_f32_e32 v48, v61, v48
	v_cvt_pk_bf16_f32 v57, v208, v209
	v_lshlrev_b32_e32 v206, 16, v55
	v_and_b32_e32 v209, 0xffff0000, v56
	v_mul_f32_e32 v207, v207, v207
	v_fmac_f32_e32 v205, v204, v204
	v_add_f32_e32 v48, v63, v48
	v_lshlrev_b32_e32 v208, 16, v56
	v_and_b32_e32 v211, 0xffff0000, v57
	v_mul_f32_e32 v209, v209, v209
	v_fmac_f32_e32 v207, v206, v206
	v_add_f32_e32 v48, v205, v48
	v_lshlrev_b32_e32 v210, 16, v57
	v_mul_f32_e32 v211, v211, v211
	v_fmac_f32_e32 v209, v208, v208
	v_add_f32_e32 v48, v207, v48
	v_add_f32_e32 v48, v209, v48
	v_fmac_f32_e32 v211, v210, v210
	v_add_f32_e32 v48, v211, v48
	ds_bpermute_b32 v49, v155, v48
	global_store_dwordx4 v[74:75], v[50:53], off
	global_store_dwordx4 v[74:75], v[54:57], off offset:256
	s_waitcnt lgkmcnt(0)
	v_add_f32_e32 v48, v48, v49
	ds_bpermute_b32 v49, v114, v48
	s_and_saveexec_b64 s[2:3], s[4:5]
	s_cbranch_execz .LBB0_440
	v_lshlrev_b64 v[50:51], 6, v[64:65]
	v_lshl_add_u64 v[50:51], s[20:21], 0, v[50:51]
	v_lshl_add_u64 v[50:51], s[26:27], 2, v[50:51]
	s_lshl_b32 s0, s42, 2
	v_lshl_add_u64 v[50:51], v[50:51], 0, s[0:1]
	s_waitcnt lgkmcnt(0)
	v_add_f32_e32 v48, v48, v49
	global_store_dword v[50:51], v48, off
;     __device__ __forceinline__ void operator()(const f32x4 (&acc)[2][2][4][2], const Unit& u, int wr, int wc, int fr, int fq) const {
;     ...
;             for (int m = 0; m < 4; ++m) { const int r = ai * HALF + wr * 64 + m * 16 + fr; bf16_t* rowp = xb + (size_t)(u.pm * BM + r) * ldc + col0; float q = 0.f;
;                 u32x4 bw[2];
; #pragma unroll
;                 for (int bj = 0; bj < 2; ++bj) bw[bj] = *(const u32x4*)(rowp + bj * HALF);
; #pragma unroll
;                 for (int bj = 0; bj < 2; ++bj) { const u32x4 b = bw[bj]; const f32x4 a0 = acc[ai][bj][m][0], a1 = acc[ai][bj][m][1];
;                     u32x4 w;
;                     w.x = pkbf(__uint_as_float(b.x << 16) + a0[0], __uint_as_float(b.x & 0xffff0000u) + a0[1]);
;                     w.y = pkbf(__uint_as_float(b.y << 16) + a0[2], __uint_as_float(b.y & 0xffff0000u) + a0[3]);
;                     w.z = pkbf(__uint_as_float(b.z << 16) + a1[0], __uint_as_float(b.z & 0xffff0000u) + a1[1]);
;                     w.w = pkbf(__uint_as_float(b.w << 16) + a1[2], __uint_as_float(b.w & 0xffff0000u) + a1[3]);
;                     *(u32x4*)(rowp + bj * HALF) = w;
;                     if (NORM) {
; #pragma unroll
;                         for (int e = 0; e < 4; ++e) { const float lo = __uint_as_float(w[e] << 16), hi = __uint_as_float(w[e] & 0xffff0000u); q += lo * lo + hi * hi; } } }
;                 if (NORM) { q += __shfl_xor(q, 16); q += __shfl_xor(q, 32); if (fq == 0) ss[(size_t)(u.pm * BM + r) * 16 + u.pn * 4 + wc] = q; } }
.LBB0_440:
	s_or_b64 exec, exec, s[2:3]
	v_add_u32_e32 v48, 0x90, v146
	s_waitcnt lgkmcnt(0)
	v_ashrrev_i32_e32 v49, 31, v48
	v_lshlrev_b64 v[50:51], 11, v[48:49]
	v_lshl_add_u64 v[50:51], s[40:41], 0, v[50:51]
	v_lshl_add_u64 v[58:59], v[144:145], 1, v[50:51]
	s_waitcnt vmcnt(18)
	v_lshlrev_b32_e32 v60, 16, v228
	v_and_b32_e32 v61, 0xffff0000, v228
	v_lshlrev_b32_e32 v228, 16, v229
	v_and_b32_e32 v229, 0xffff0000, v229
	v_lshlrev_b32_e32 v62, 16, v230
	v_and_b32_e32 v63, 0xffff0000, v230
	v_lshlrev_b32_e32 v230, 16, v231
	v_and_b32_e32 v231, 0xffff0000, v231
	s_waitcnt vmcnt(17)
	v_lshlrev_b32_e32 v64, 16, v232
	v_and_b32_e32 v65, 0xffff0000, v232
	v_lshlrev_b32_e32 v232, 16, v233
	v_and_b32_e32 v233, 0xffff0000, v233
	v_lshlrev_b32_e32 v66, 16, v234
	v_and_b32_e32 v67, 0xffff0000, v234
	v_lshlrev_b32_e32 v234, 16, v235
	v_and_b32_e32 v235, 0xffff0000, v235
	v_pk_add_f32 v[44:45], v[44:45], v[60:61]
	v_pk_add_f32 v[46:47], v[46:47], v[228:229]
	v_pk_add_f32 v[40:41], v[40:41], v[62:63]
	v_pk_add_f32 v[42:43], v[42:43], v[230:231]
	v_pk_add_f32 v[230:231], v[38:39], v[232:233]
	v_pk_add_f32 v[32:33], v[32:33], v[66:67]
	v_pk_add_f32 v[232:233], v[34:35], v[234:235]
	v_cvt_pk_bf16_f32 v34, v44, v45
	v_cvt_pk_bf16_f32 v35, v46, v47
	v_pk_add_f32 v[228:229], v[36:37], v[64:65]
	v_cvt_pk_bf16_f32 v36, v40, v41
	v_cvt_pk_bf16_f32 v37, v42, v43
	v_cvt_pk_bf16_f32 v40, v32, v33
	v_and_b32_e32 v33, 0xffff0000, v34
	v_and_b32_e32 v43, 0xffff0000, v35
	v_lshlrev_b32_e32 v32, 16, v34
	v_lshlrev_b32_e32 v42, 16, v35
	v_and_b32_e32 v45, 0xffff0000, v36
	v_mul_f32_e32 v33, v33, v33
	v_mul_f32_e32 v43, v43, v43
	v_cvt_pk_bf16_f32 v38, v228, v229
	v_lshlrev_b32_e32 v44, 16, v36
	v_and_b32_e32 v47, 0xffff0000, v37
	v_mul_f32_e32 v45, v45, v45
	v_fmac_f32_e32 v33, v32, v32
	v_fmac_f32_e32 v43, v42, v42
	v_cvt_pk_bf16_f32 v39, v230, v231
	v_lshlrev_b32_e32 v46, 16, v37
	v_and_b32_e32 v229, 0xffff0000, v38
	v_mul_f32_e32 v47, v47, v47
	v_fmac_f32_e32 v45, v44, v44
	v_add_f32_e32 v32, v33, v43
	v_lshlrev_b32_e32 v228, 16, v38
	v_and_b32_e32 v231, 0xffff0000, v39
	v_mul_f32_e32 v229, v229, v229
	v_fmac_f32_e32 v47, v46, v46
	v_add_f32_e32 v32, v45, v32
	v_cvt_pk_bf16_f32 v41, v232, v233
	v_lshlrev_b32_e32 v230, 16, v39
	v_and_b32_e32 v233, 0xffff0000, v40
	v_mul_f32_e32 v231, v231, v231
	v_fmac_f32_e32 v229, v228, v228
	v_add_f32_e32 v32, v47, v32
	v_lshlrev_b32_e32 v232, 16, v40
	v_and_b32_e32 v235, 0xffff0000, v41
	v_mul_f32_e32 v233, v233, v233
	v_fmac_f32_e32 v231, v230, v230
	v_add_f32_e32 v32, v229, v32
	v_lshlrev_b32_e32 v234, 16, v41
	v_mul_f32_e32 v235, v235, v235
	v_fmac_f32_e32 v233, v232, v232
	v_add_f32_e32 v32, v231, v32
	v_add_f32_e32 v32, v233, v32
	v_fmac_f32_e32 v235, v234, v234
	v_add_f32_e32 v32, v235, v32
	ds_bpermute_b32 v33, v155, v32
	global_store_dwordx4 v[58:59], v[34:37], off
	global_store_dwordx4 v[58:59], v[38:41], off offset:256
	s_waitcnt lgkmcnt(0)
	v_add_f32_e32 v32, v32, v33
	ds_bpermute_b32 v33, v114, v32
	s_and_saveexec_b64 s[2:3], s[4:5]
	s_cbranch_execz .LBB0_442
	v_lshlrev_b64 v[34:35], 6, v[48:49]
	v_lshl_add_u64 v[34:35], s[20:21], 0, v[34:35]
	v_lshl_add_u64 v[34:35], s[26:27], 2, v[34:35]
	s_lshl_b32 s0, s42, 2
	v_lshl_add_u64 v[34:35], v[34:35], 0, s[0:1]
	s_waitcnt lgkmcnt(0)
	v_add_f32_e32 v32, v32, v33
	global_store_dword v[34:35], v32, off
.LBB0_442:
	s_or_b64 exec, exec, s[2:3]
	v_add_u32_e32 v32, 0xa0, v146
	s_waitcnt lgkmcnt(0)
	v_ashrrev_i32_e32 v33, 31, v32
	v_lshlrev_b64 v[34:35], 11, v[32:33]
	v_lshl_add_u64 v[34:35], s[40:41], 0, v[34:35]
	v_lshl_add_u64 v[42:43], v[144:145], 1, v[34:35]
	s_waitcnt vmcnt(19)
	v_lshlrev_b32_e32 v44, 16, v236
	v_and_b32_e32 v45, 0xffff0000, v236
	v_lshlrev_b32_e32 v236, 16, v237
	v_and_b32_e32 v237, 0xffff0000, v237
	v_lshlrev_b32_e32 v46, 16, v238
	v_and_b32_e32 v47, 0xffff0000, v238
	v_lshlrev_b32_e32 v238, 16, v239
	v_and_b32_e32 v239, 0xffff0000, v239
	s_waitcnt vmcnt(18)
	v_lshlrev_b32_e32 v48, 16, v240
	v_and_b32_e32 v49, 0xffff0000, v240
	v_lshlrev_b32_e32 v240, 16, v241
	v_and_b32_e32 v241, 0xffff0000, v241
	v_lshlrev_b32_e32 v50, 16, v242
	v_and_b32_e32 v51, 0xffff0000, v242
	v_lshlrev_b32_e32 v242, 16, v243
	v_and_b32_e32 v243, 0xffff0000, v243
	v_pk_add_f32 v[28:29], v[28:29], v[44:45]
	v_pk_add_f32 v[30:31], v[30:31], v[236:237]
	v_pk_add_f32 v[24:25], v[24:25], v[46:47]
	v_pk_add_f32 v[26:27], v[26:27], v[238:239]
	v_pk_add_f32 v[238:239], v[22:23], v[240:241]
	v_pk_add_f32 v[16:17], v[16:17], v[50:51]
	v_pk_add_f32 v[240:241], v[18:19], v[242:243]
	v_cvt_pk_bf16_f32 v18, v28, v29
	v_cvt_pk_bf16_f32 v19, v30, v31
	v_pk_add_f32 v[236:237], v[20:21], v[48:49]
	v_cvt_pk_bf16_f32 v20, v24, v25
	v_cvt_pk_bf16_f32 v21, v26, v27
	v_cvt_pk_bf16_f32 v24, v16, v17
	v_and_b32_e32 v17, 0xffff0000, v18
	v_and_b32_e32 v27, 0xffff0000, v19
	v_lshlrev_b32_e32 v16, 16, v18
	v_lshlrev_b32_e32 v26, 16, v19
	v_and_b32_e32 v29, 0xffff0000, v20
	v_mul_f32_e32 v17, v17, v17
	v_mul_f32_e32 v27, v27, v27
	v_cvt_pk_bf16_f32 v22, v236, v237
	v_lshlrev_b32_e32 v28, 16, v20
	v_and_b32_e32 v31, 0xffff0000, v21
	v_mul_f32_e32 v29, v29, v29
	v_fmac_f32_e32 v17, v16, v16
	v_fmac_f32_e32 v27, v26, v26
	v_cvt_pk_bf16_f32 v23, v238, v239
	v_lshlrev_b32_e32 v30, 16, v21
	v_and_b32_e32 v237, 0xffff0000, v22
	v_mul_f32_e32 v31, v31, v31
	v_fmac_f32_e32 v29, v28, v28
	v_add_f32_e32 v16, v17, v27
	v_lshlrev_b32_e32 v236, 16, v22
	v_and_b32_e32 v239, 0xffff0000, v23
	v_mul_f32_e32 v237, v237, v237
	v_fmac_f32_e32 v31, v30, v30
	v_add_f32_e32 v16, v29, v16
	v_cvt_pk_bf16_f32 v25, v240, v241
	v_lshlrev_b32_e32 v238, 16, v23
	v_and_b32_e32 v241, 0xffff0000, v24
	v_mul_f32_e32 v239, v239, v239
	v_fmac_f32_e32 v237, v236, v236
	v_add_f32_e32 v16, v31, v16
	v_lshlrev_b32_e32 v240, 16, v24
	v_and_b32_e32 v243, 0xffff0000, v25
	v_mul_f32_e32 v241, v241, v241
	v_fmac_f32_e32 v239, v238, v238
	v_add_f32_e32 v16, v237, v16
	v_lshlrev_b32_e32 v242, 16, v25
	v_mul_f32_e32 v243, v243, v243
	v_fmac_f32_e32 v241, v240, v240
	v_add_f32_e32 v16, v239, v16
	v_add_f32_e32 v16, v241, v16
	v_fmac_f32_e32 v243, v242, v242
	v_add_f32_e32 v16, v243, v16
	ds_bpermute_b32 v17, v155, v16
	global_store_dwordx4 v[42:43], v[18:21], off
	global_store_dwordx4 v[42:43], v[22:25], off offset:256
	s_waitcnt lgkmcnt(0)
	v_add_f32_e32 v16, v16, v17
	ds_bpermute_b32 v17, v114, v16
	s_and_saveexec_b64 s[2:3], s[4:5]
	s_cbranch_execz .LBB0_444
	v_lshlrev_b64 v[18:19], 6, v[32:33]
	v_lshl_add_u64 v[18:19], s[20:21], 0, v[18:19]
	v_lshl_add_u64 v[18:19], s[26:27], 2, v[18:19]
	s_lshl_b32 s0, s42, 2
	v_lshl_add_u64 v[18:19], v[18:19], 0, s[0:1]
	s_waitcnt lgkmcnt(0)
	v_add_f32_e32 v16, v16, v17
	global_store_dword v[18:19], v16, off
